# v21 + P6 residual prefetch: waves 1-7 issue 31 of their 32 x-tile loads before the P5->P6 grid barrier
# baseline (speedup 1.0000x reference)
; #define LAS __attribute__((address_space(3)))
; __global__ void __launch_bounds__(NWAVES * 64, 2) mega_fwd(Args args) {
;     ...
;     F.lds = (LAS unsigned char*)lds;
;     F.tid = threadIdx.x; F.lane = F.tid & 63; F.wave = __builtin_amdgcn_readfirstlane(F.tid >> 6);
;     F.G = gridDim.x; { const int bx = blockIdx.x; F.vcu = (F.G % 8 == 0) ? (bx % 8) * (F.G / 8) + bx / 8 : bx; }
_Z8mega_fwd4Args:
	s_load_dword s52, s[0:1], 0x88
	s_mov_b32 s99, 0
	s_add_u32 s4, s0, 0x88
	s_addc_u32 s5, s1, 0
	v_readfirstlane_b32 s82, v0
	v_writelane_b32 v255, s4, 0
	s_waitcnt lgkmcnt(0)
	s_and_b32 s3, s52, 7
	s_cmp_lg_u32 s3, 0
	v_writelane_b32 v255, s5, 1
	v_writelane_b32 v255, s2, 2
	v_writelane_b32 v255, s2, 3
	s_nop 1
	v_writelane_b32 v255, s3, 4
	s_cbranch_scc1 .LBB0_2
	v_readlane_b32 s5, v255, 2
	s_ashr_i32 s3, s5, 31
	s_lshr_b32 s3, s3, 29
	s_add_i32 s3, s5, s3
	s_and_b32 s4, s3, -8
	s_ashr_i32 s2, s52, 3
	s_sub_i32 s4, s5, s4
	s_mul_i32 s2, s2, s4
	s_ashr_i32 s3, s3, 3
	s_add_i32 s2, s2, s3
	v_writelane_b32 v255, s2, 3
	s_nop 1
	v_writelane_b32 v255, s3, 4

; __device__ __forceinline__ unsigned xb_ld(unsigned* p)              { return __hip_atomic_load(p, __ATOMIC_RELAXED, __HIP_MEMORY_SCOPE_AGENT); }
; __device__ __forceinline__ unsigned xb_add(unsigned* p, unsigned v) { return __hip_atomic_fetch_add(p, v, __ATOMIC_RELAXED, __HIP_MEMORY_SCOPE_AGENT); }
;     __device__ __forceinline__ void init(f32x4 (&acc)[2][2][4][2], const Unit& u, int wr, int wc, int fr, int fq) const {
;         const int col0 = u.pn * BM + wc * 32 + 4 * fq;
; #pragma unroll
;         for (int ai = 0; ai < 2; ++ai)
; #pragma unroll
;             for (int m = 0; m < 4; ++m) { const size_t off = (size_t)(u.pm * BM + ai * HALF + wr * 64 + m * 16 + fr) * DM + col0;
; #pragma unroll
;                 for (int bj = 0; bj < 2; ++bj)
; #pragma unroll
;                     for (int n = 0; n < 2; ++n) acc[ai][bj][m][n] = __builtin_nontemporal_load((const f32x4*)(x + off + bj * HALF + n * 16)); }
;     }
; __device__ __forceinline__ void xcd_barrier(const XcdBarrier& b) {
;     asm volatile("s_waitcnt vmcnt(0)" ::: "memory");
;     __syncthreads();
;     if (threadIdx.x == 0) {
;         unsigned* bar = b.bar;
;         __builtin_amdgcn_s_waitcnt(0);
;         unsigned nloc = b.st[0], nx = b.st[1];
;         if (nloc == 0u) { xcd_barrier_complete(bar, b.x, nloc, nx); b.st[0] = nloc; b.st[1] = nx; }
;         const unsigned old = xb_add(&bar[XB_XSUB(b.x)], 1u);
;         const unsigned gen = old / nloc;
;         if (old + 1u == (gen + 1u) * nloc) {
;             __builtin_amdgcn_fence(__ATOMIC_RELEASE, "agent");
;             asm volatile("s_waitcnt vmcnt(0)" ::: "memory");
;             const unsigned og = xb_add(&bar[XB_TOP], 1u);
;             const unsigned tg = og / nx;
;             if (og + 1u == (tg + 1u) * nx) xb_add(&bar[XB_TOPGEN], 1u);
;             else XB_SPIN(xb_ld(&bar[XB_TOPGEN]) == tg, bar);
;             __builtin_amdgcn_fence(__ATOMIC_ACQUIRE, "agent");
;             xb_add(&bar[XB_XGEN(b.x)], 1u);
;             asm volatile("s_waitcnt vmcnt(0)" ::: "memory");
;         } else {
;             XB_SPIN(xb_ld(&bar[XB_XGEN(b.x)]) == gen, bar);
;             __builtin_amdgcn_fence(__ATOMIC_ACQUIRE, "agent");
;             asm volatile("s_waitcnt vmcnt(0)" ::: "memory");
;         }
;     }
;     __syncthreads();
; }
.LBB0_948:
	v_readlane_b32 s4, v255, 5
	v_readlane_b32 s5, v255, 6
	s_cmp_lt_i32 s5, 7
	s_cbranch_scc1 .LBB0_998
	v_readlane_b32 s0, v255, 11
	v_readlane_b32 s1, v255, 12
	s_or_b32 s0, s0, s1
	v_readfirstlane_b32 s1, v0
	s_lshr_b32 s1, s1, 6
	s_cmp_eq_u32 s0, 0
	s_cselect_b32 s0, 1, 0
	s_cmp_lg_u32 s1, 0
	s_cselect_b32 s99, s0, 0
	s_cmp_eq_u32 s99, 0
	s_cbranch_scc1 .Lxpf_none
	v_readlane_b32 s0, v255, 2
	s_and_b32 s2, s0, 7
	s_lshr_b32 s3, s0, 3
	s_lshl_b32 s2, s2, 2
	s_and_b32 s6, s3, 3
	s_add_i32 s2, s2, s6
	s_lshr_b32 s3, s3, 2
	s_and_b32 s6, s1, 3
	s_lshr_b32 s7, s1, 2
	s_lshl_b32 s2, s2, 8
	s_lshl_b32 s7, s7, 6
	s_add_i32 s2, s2, s7
	s_lshl_b32 s3, s3, 8
	s_lshl_b32 s6, s6, 5
	s_add_i32 s3, s3, s6
	v_and_b32_e32 v200, 15, v0
	v_lshrrev_b32_e32 v201, 2, v0
	v_and_b32_e32 v201, 12, v201
	v_add_u32_e32 v200, s2, v200
	v_add_u32_e32 v201, s3, v201
	v_lshlrev_b32_e32 v200, 13, v200
	v_lshl_add_u32 v200, v201, 2, v200
	global_load_dwordx4 v[126:129], v200, s[36:37] nt
	global_load_dwordx4 v[118:121], v200, s[36:37] offset:64 nt
	global_load_dwordx4 v[110:113], v200, s[36:37] offset:512 nt
	global_load_dwordx4 v[106:109], v200, s[36:37] offset:576 nt
	v_add_u32_e32 v201, 0x20000, v200
	global_load_dwordx4 v[122:125], v201, s[36:37] nt
	global_load_dwordx4 v[114:117], v201, s[36:37] offset:64 nt
	global_load_dwordx4 v[102:105], v201, s[36:37] offset:512 nt
	global_load_dwordx4 v[94:97], v201, s[36:37] offset:576 nt
	v_add_u32_e32 v201, 0x40000, v200
	global_load_dwordx4 v[98:101], v201, s[36:37] nt
	global_load_dwordx4 v[90:93], v201, s[36:37] offset:64 nt
	global_load_dwordx4 v[82:85], v201, s[36:37] offset:512 nt
	global_load_dwordx4 v[74:77], v201, s[36:37] offset:576 nt
	v_add_u32_e32 v201, 0x60000, v200
	global_load_dwordx4 v[86:89], v201, s[36:37] nt
	global_load_dwordx4 v[78:81], v201, s[36:37] offset:64 nt
	global_load_dwordx4 v[70:73], v201, s[36:37] offset:512 nt
	global_load_dwordx4 v[66:69], v201, s[36:37] offset:576 nt
	v_add_u32_e32 v201, 0x100000, v200
	global_load_dwordx4 v[62:65], v201, s[36:37] nt
	global_load_dwordx4 v[58:61], v201, s[36:37] offset:64 nt
	global_load_dwordx4 v[50:53], v201, s[36:37] offset:512 nt
	global_load_dwordx4 v[42:45], v201, s[36:37] offset:576 nt
	v_add_u32_e32 v201, 0x120000, v200
	global_load_dwordx4 v[54:57], v201, s[36:37] nt
	global_load_dwordx4 v[46:49], v201, s[36:37] offset:64 nt
	global_load_dwordx4 v[38:41], v201, s[36:37] offset:512 nt
	global_load_dwordx4 v[30:33], v201, s[36:37] offset:576 nt
	v_add_u32_e32 v201, 0x140000, v200
	global_load_dwordx4 v[34:37], v201, s[36:37] nt
	global_load_dwordx4 v[26:29], v201, s[36:37] offset:64 nt
	global_load_dwordx4 v[18:21], v201, s[36:37] offset:512 nt
	global_load_dwordx4 v[10:13], v201, s[36:37] offset:576 nt
	v_add_u32_e32 v201, 0x160000, v200
	global_load_dwordx4 v[22:25], v201, s[36:37] nt
	global_load_dwordx4 v[14:17], v201, s[36:37] offset:64 nt
	global_load_dwordx4 v[6:9], v201, s[36:37] offset:512 nt
	v_cmp_eq_u32_e32 vcc, 0, v0
	s_branch .Lxpf_join
.Lxpf_none:
	s_waitcnt vmcnt(0)
	v_cmp_eq_u32_e32 vcc, 0, v0
	s_waitcnt vmcnt(0)
.Lxpf_join:
	s_barrier
	s_and_saveexec_b64 s[2:3], vcc
	s_cbranch_execz .LBB0_997
	v_readlane_b32 s0, v255, 8
	s_waitcnt vmcnt(0) expcnt(0) lgkmcnt(0)
	s_nop 0
	v_mov_b32_e32 v1, s0
	ds_read_b32 v3, v1
	ds_read_b32 v1, v1 offset:4
	s_waitcnt lgkmcnt(1)
	v_cmp_ne_u32_e32 vcc, 0, v3
	s_cbranch_vccnz .LBB0_965
	v_readlane_b32 s4, v255, 0
	v_readlane_b32 s5, v255, 1
	s_load_dwordx2 s[0:1], s[4:5], 0x4
	s_add_u32 s4, s26, 0x4200
	s_addc_u32 s5, s27, 0
	s_add_u32 s6, s26, 0x4400
	s_addc_u32 s7, s27, 0
	s_add_u32 s8, s26, 0x4500
	s_addc_u32 s9, s27, 0
	s_add_u32 s12, s26, 0x4600
	s_addc_u32 s13, s27, 0
	s_add_u32 s14, s26, 0x4700
	s_addc_u32 s15, s27, 0
	s_add_u32 s16, s26, 0x4800
	s_addc_u32 s17, s27, 0
	s_add_u32 s18, s26, 0x4900
	s_addc_u32 s19, s27, 0
	s_add_u32 s20, s26, 0x4a00
	s_addc_u32 s21, s27, 0
	s_add_u32 s28, s26, 0x4b00
	s_addc_u32 s29, s27, 0
	s_add_u32 s30, s26, 0x4c00
	s_addc_u32 s31, s27, 0
	s_add_u32 s38, s26, 0x4d00
	s_addc_u32 s39, s27, 0
	s_add_u32 s40, s26, 0x4e00
	s_addc_u32 s41, s27, 0
	s_add_u32 s42, s26, 0x4f00
	s_addc_u32 s43, s27, 0
	s_add_u32 s44, s26, 0x5000
	s_addc_u32 s45, s27, 0
	s_add_u32 s46, s26, 0x5100
	s_addc_u32 s47, s27, 0
	s_add_u32 s48, s26, 0x5200
	s_addc_u32 s49, s27, 0
	s_waitcnt lgkmcnt(0)
	s_mul_i32 s0, s0, s52
	s_add_u32 s50, s26, 0x5300
	s_mul_i32 s0, s0, s1
	s_addc_u32 s51, s27, 0
	s_mov_b32 s1, 1
	v_mov_b32_e32 v17, 0
	s_branch .LBB0_953

;     __device__ __forceinline__ void init(f32x4 (&acc)[2][2][4][2], const Unit& u, int wr, int wc, int fr, int fq) const {
;         const int col0 = u.pn * BM + wc * 32 + 4 * fq;
; #pragma unroll
;         for (int ai = 0; ai < 2; ++ai)
; #pragma unroll
;             for (int m = 0; m < 4; ++m) { const size_t off = (size_t)(u.pm * BM + ai * HALF + wr * 64 + m * 16 + fr) * DM + col0;
; #pragma unroll
;                 for (int bj = 0; bj < 2; ++bj)
; #pragma unroll
;                     for (int n = 0; n < 2; ++n) acc[ai][bj][m][n] = __builtin_nontemporal_load((const f32x4*)(x + off + bj * HALF + n * 16)); }
;     }
; template <class Epi, class Sched, bool ALIGN_EPI>
; __device__ __forceinline__ void gemm_phase(PG8_LAS unsigned char* lds, const Gemm g, const Sched& S, const Epi& E) {
;     const int tid = threadIdx.x, wid = __builtin_amdgcn_readfirstlane(tid >> 6), lane = tid & 63, wr = wid >> 2, wc = wid & 3, fr = lane & 15, fq = lane >> 4;
;     const int lda = g.lda, ldb = g.ldb;
;     unsigned voffA[2], voffB[2];
; #pragma unroll
;     for (int i = 0; i < 2; ++i) { int R, C; stage_rc(tid * 16 + i * 8192, R, C); const int Rb = Epi::PERM ? ((R & ~31) + perm32(R & 31)) : R;
;         voffA[i] = (unsigned)(R * lda + C) * 2u; voffB[i] = (unsigned)(Rb * ldb + C) * 2u; }
;     const size_t kstep = (size_t)(BK * 2);
;     const size_t hstepA = (size_t)HALF * lda * 2, hstepB = (size_t)HALF * ldb * 2;
;     const unsigned ldsw = (unsigned)wid * 1024u;
;     const int aoff = lds_byte(wr * 64 + fr, fq * 8), boff = lds_byte(wc * 32 + fr, fq * 8);
;     ...
;     Unit cur, nxt; int ui = 0;
;     if (!S.next(0, cur)) return;
;     f32x4 acc[2][2][4][2];
;     if constexpr (Epi::HAS_INIT) E.init(acc, cur, wr, wc, fr, fq);
;     else {
; #pragma unroll
;     for (int a = 0; a < 2; ++a)
; #pragma unroll
;         for (int b = 0; b < 2; ++b)
; #pragma unroll
;             for (int m = 0; m < 4; ++m)
; #pragma unroll
;                 for (int n = 0; n < 2; ++n) acc[a][b][m][n] = (f32x4){0.f, 0.f, 0.f, 0.f};
;     }
;     bf16x8 At[4][2], B0[2][2], B1[2][2];
;     const char* cA = PG8_UA(cur); const char* cB = PG8_UB(cur);
;     if constexpr (Sched::GATED) { S.gate(cur, wid == 0); __builtin_amdgcn_s_barrier(); }
;     PG8_STAGE(PG8_SB(0, 0), cB, voffB); PG8_STAGE(PG8_SB(0, 1), cB + hstepB, voffB); PG8_STAGE(PG8_SA(0, 0), cA, voffA); PG8_STAGE(PG8_SA(0, 1), cA + hstepA, voffA);
.LBB0_1027:
	v_lshlrev_b32_e32 v1, 4, v0
	s_ashr_i32 s2, s5, 3
	s_cmp_lg_u32 s99, 0
	s_cbranch_scc1 .Lxpf_w
	s_waitcnt vmcnt(0)
.Lxpf_w:
	v_and_b32_e32 v2, 32, v0
	v_or_b32_e32 v145, 0x2000, v1
	v_bfe_u32 v144, v0, 2, 4
	v_bitop3_b32 v142, v1, v2, 48 bitop3:0x6c
	v_lshrrev_b32_e32 v1, 7, v145
	s_movk_i32 s3, 0x70
	s_add_i32 s2, s4, s2
	v_and_or_b32 v1, v1, s3, v144
	s_ashr_i32 s3, s2, 31
	s_lshr_b32 s3, s3, 27
	s_add_i32 s3, s2, s3
	s_ashr_i32 s4, s3, 5
	s_andn2_b32 s3, s3, 31
	s_sub_i32 s3, s2, s3
	s_bfe_i32 s2, s3, 0x80000
	s_bfe_u32 s2, s2, 0x2000d
	s_add_i32 s5, s3, s2
	s_bfe_i32 s2, s5, 0x80000
	s_and_b32 s5, s5, 0xfc
	s_sext_i32_i16 s6, s2
	s_sub_i32 s3, s3, s5
	s_bfe_u32 s42, s34, 0x20006
	s_lshl_b32 s4, s4, 2
	s_sext_i32_i8 s3, s3
	s_ashr_i32 s12, s6, 2
	v_lshrrev_b32_e32 v3, 2, v0
	v_and_b32_e32 v143, 64, v0
	v_lshrrev_b32_e32 v4, 3, v0
	s_lshl_b32 s33, s42, 5
	s_add_i32 s8, s4, s3
	s_lshl_b32 s3, s12, 8
	v_or_b32_e32 v2, v142, v143
	v_and_or_b32 v4, v4, 48, v144
	s_lshr_b32 s35, s34, 8
	v_and_b32_e32 v154, 15, v0
	s_or_b32 s3, s3, s33
	v_and_b32_e32 v153, 12, v3
	v_lshl_or_b32 v130, v4, 12, v2
	v_lshl_or_b32 v132, v1, 12, v2
	v_lshl_or_b32 v152, s35, 6, v154
	v_or_b32_e32 v2, s3, v153
	s_lshl_b32 s3, s8, 8
	v_add_u32_e32 v4, s3, v152
	v_ashrrev_i32_e32 v5, 31, v4
	v_ashrrev_i32_e32 v3, 31, v2
	v_lshlrev_b64 v[4:5], 13, v[4:5]
	v_lshl_add_u64 v[4:5], s[36:37], 0, v[4:5]
	v_lshlrev_b64 v[2:3], 2, v[2:3]
	v_lshl_add_u64 v[4:5], v[4:5], 0, v[2:3]
	v_or_b32_e32 v151, 16, v152
	s_cmp_lg_u32 s99, 0
	s_cbranch_scc1 .Lxpf_a0
	global_load_dwordx4 v[126:129], v[4:5], off nt
	global_load_dwordx4 v[118:121], v[4:5], off offset:64 nt
	global_load_dwordx4 v[110:113], v[4:5], off offset:512 nt
	global_load_dwordx4 v[106:109], v[4:5], off offset:576 nt
.Lxpf_a0:
	v_add_u32_e32 v4, s3, v151
	v_ashrrev_i32_e32 v5, 31, v4
	v_lshlrev_b64 v[4:5], 13, v[4:5]
	v_lshl_add_u64 v[4:5], s[36:37], 0, v[4:5]
	v_lshl_add_u64 v[4:5], v[4:5], 0, v[2:3]
	v_or_b32_e32 v150, 32, v152
	s_cmp_lg_u32 s99, 0
	s_cbranch_scc1 .Lxpf_a1
	global_load_dwordx4 v[122:125], v[4:5], off nt
	global_load_dwordx4 v[114:117], v[4:5], off offset:64 nt
	global_load_dwordx4 v[102:105], v[4:5], off offset:512 nt
	global_load_dwordx4 v[94:97], v[4:5], off offset:576 nt
.Lxpf_a1:
	v_add_u32_e32 v4, s3, v150
	v_ashrrev_i32_e32 v5, 31, v4
	v_lshlrev_b64 v[4:5], 13, v[4:5]
	v_lshl_add_u64 v[4:5], s[36:37], 0, v[4:5]
	v_lshl_add_u64 v[4:5], v[4:5], 0, v[2:3]
	v_or_b32_e32 v149, 48, v152
	s_cmp_lg_u32 s99, 0
	s_cbranch_scc1 .Lxpf_a2
	global_load_dwordx4 v[98:101], v[4:5], off nt
	global_load_dwordx4 v[90:93], v[4:5], off offset:64 nt
	global_load_dwordx4 v[82:85], v[4:5], off offset:512 nt
	global_load_dwordx4 v[74:77], v[4:5], off offset:576 nt
.Lxpf_a2:
	v_add_u32_e32 v4, s3, v149
	v_ashrrev_i32_e32 v5, 31, v4
	v_lshlrev_b64 v[4:5], 13, v[4:5]
	v_lshl_add_u64 v[4:5], s[36:37], 0, v[4:5]
	v_lshl_add_u64 v[4:5], v[4:5], 0, v[2:3]
	v_add_u32_e32 v148, 0x80, v152
	s_cmp_lg_u32 s99, 0
	s_cbranch_scc1 .Lxpf_a3
	global_load_dwordx4 v[86:89], v[4:5], off nt
	global_load_dwordx4 v[78:81], v[4:5], off offset:64 nt
	global_load_dwordx4 v[70:73], v[4:5], off offset:512 nt
	global_load_dwordx4 v[66:69], v[4:5], off offset:576 nt
.Lxpf_a3:
	v_add_u32_e32 v4, s3, v148
	v_ashrrev_i32_e32 v5, 31, v4
	v_lshlrev_b64 v[4:5], 13, v[4:5]
	v_lshl_add_u64 v[4:5], s[36:37], 0, v[4:5]
	v_lshl_add_u64 v[4:5], v[4:5], 0, v[2:3]
	v_add_u32_e32 v147, 0x90, v152
	s_cmp_lg_u32 s99, 0
	s_cbranch_scc1 .Lxpf_a4
	global_load_dwordx4 v[62:65], v[4:5], off nt
	global_load_dwordx4 v[58:61], v[4:5], off offset:64 nt
	global_load_dwordx4 v[50:53], v[4:5], off offset:512 nt
	global_load_dwordx4 v[42:45], v[4:5], off offset:576 nt
.Lxpf_a4:
	v_add_u32_e32 v4, s3, v147
	v_ashrrev_i32_e32 v5, 31, v4
	v_lshlrev_b64 v[4:5], 13, v[4:5]
	v_lshl_add_u64 v[4:5], s[36:37], 0, v[4:5]
	v_lshl_add_u64 v[4:5], v[4:5], 0, v[2:3]
	v_add_u32_e32 v146, 0xa0, v152
	s_cmp_lg_u32 s99, 0
	s_cbranch_scc1 .Lxpf_a5
	global_load_dwordx4 v[54:57], v[4:5], off nt
	global_load_dwordx4 v[46:49], v[4:5], off offset:64 nt
	global_load_dwordx4 v[38:41], v[4:5], off offset:512 nt
	global_load_dwordx4 v[30:33], v[4:5], off offset:576 nt
.Lxpf_a5:
	v_add_u32_e32 v4, s3, v146
	v_ashrrev_i32_e32 v5, 31, v4
	v_lshlrev_b64 v[4:5], 13, v[4:5]
	v_lshl_add_u64 v[4:5], s[36:37], 0, v[4:5]
	v_lshl_add_u64 v[4:5], v[4:5], 0, v[2:3]
	v_add_u32_e32 v1, 0xb0, v152
	s_lshr_b32 s2, s6, 2
	s_cmp_lg_u32 s99, 0
	s_cbranch_scc1 .Lxpf_a6
	global_load_dwordx4 v[34:37], v[4:5], off nt
	global_load_dwordx4 v[26:29], v[4:5], off offset:64 nt
	global_load_dwordx4 v[18:21], v[4:5], off offset:512 nt
	global_load_dwordx4 v[10:13], v[4:5], off offset:576 nt
.Lxpf_a6:
	v_add_u32_e32 v4, s3, v1
	s_lshr_b32 s13, s34, 6
	v_ashrrev_i32_e32 v5, 31, v4
	s_ashr_i32 s9, s8, 31
	s_bfe_i64 s[2:3], s[2:3], 0x100000
	s_lshl_b32 s44, s13, 10
	v_lshlrev_b64 v[4:5], 13, v[4:5]
	s_lshl_b64 s[4:5], s[8:9], 20
	s_lshl_b64 s[2:3], s[2:3], 20
	v_lshl_add_u64 v[4:5], s[36:37], 0, v[4:5]
	s_add_u32 s36, s10, s2
	s_addc_u32 s37, s11, s3
	s_add_i32 s9, s44, 0
	v_lshl_add_u64 v[2:3], v[4:5], 0, v[2:3]
	s_add_i32 m0, s9, 0x10000
	s_cmp_lg_u32 s99, 0
	s_cbranch_scc1 .Lxpf_a7
	global_load_dwordx4 v[22:25], v[2:3], off nt
	global_load_dwordx4 v[14:17], v[2:3], off offset:64 nt
	global_load_dwordx4 v[6:9], v[2:3], off offset:512 nt
.Lxpf_a7:
	s_nop 0
	global_load_dwordx4 v[2:5], v[2:3], off offset:576 nt
	v_mov_b32_e32 v131, 0
	global_load_lds_dwordx4 v130, s[36:37]
	s_add_i32 m0, s9, 0x12000
	s_add_u32 s2, s36, 0x80000
	global_load_lds_dwordx4 v132, s[36:37]
	s_addc_u32 s3, s37, 0
	s_add_i32 m0, s9, 0x14000
	v_mov_b32_e32 v133, v131
	global_load_lds_dwordx4 v130, s[2:3]
	s_add_i32 m0, s9, 0x16000
	s_add_u32 s6, s0, s4
	s_addc_u32 s7, s1, s5
	s_add_i32 s45, s9, 0x2000
	global_load_lds_dwordx4 v132, s[2:3]
	s_mov_b32 m0, s9
	s_add_u32 s2, s6, 0x80000
	global_load_lds_dwordx4 v130, s[6:7]
	s_mov_b32 m0, s45
	s_addc_u32 s3, s7, 0
	s_add_i32 s46, s9, 0x4000
	global_load_lds_dwordx4 v132, s[6:7]
	s_mov_b32 m0, s46
	s_add_i32 s47, s9, 0x6000
	global_load_lds_dwordx4 v130, s[2:3]
	s_mov_b32 m0, s47
	s_mov_b32 s48, 0
	global_load_lds_dwordx4 v132, s[2:3]
	v_lshl_add_u64 v[140:141], s[36:37], 0, v[130:131]
	v_lshl_add_u64 v[138:139], s[36:37], 0, v[132:133]
	v_lshl_add_u64 v[136:137], s[6:7], 0, v[130:131]
	s_cmp_lg_u32 s35, 1
	v_lshl_add_u64 v[134:135], s[6:7], 0, v[132:133]
	s_cbranch_scc1 .LBB0_1029
	s_barrier

; #define LAS __attribute__((address_space(3)))
; __global__ void __launch_bounds__(NWAVES * 64, 2) mega_fwd(Args args) {
;     extern __shared__ __attribute__((aligned(16))) unsigned char lds[];
;     Frame F;
;     F.lds = (LAS unsigned char*)lds;
;     F.tid = threadIdx.x; F.lane = F.tid & 63; F.wave = __builtin_amdgcn_readfirstlane(F.tid >> 6);
;     F.G = gridDim.x; { const int bx = blockIdx.x; F.vcu = (F.G % 8 == 0) ? (bx % 8) * (F.G / 8) + bx / 8 : bx; }
;     unsigned char* ws = args.ws;
;     for (int u = F.tid; u < (LDS_BYTES - LDSCTL_OFF) / 4; u += NWAVES * 64) ((LAS unsigned*)(F.lds + LDSCTL_OFF))[u] = 0u;
;     __syncthreads();
	.amdhsa_kernel _Z8mega_fwd4Args
		.amdhsa_group_segment_fixed_size 0
		.amdhsa_private_segment_fixed_size 0
		.amdhsa_kernarg_size 392
		.amdhsa_user_sgpr_count 2
		.amdhsa_user_sgpr_dispatch_ptr 0
		.amdhsa_user_sgpr_queue_ptr 0
		.amdhsa_user_sgpr_kernarg_segment_ptr 1
		.amdhsa_user_sgpr_dispatch_id 0
		.amdhsa_user_sgpr_kernarg_preload_length 0
		.amdhsa_user_sgpr_kernarg_preload_offset 0
		.amdhsa_user_sgpr_private_segment_size 0
		.amdhsa_uses_dynamic_stack 0
		.amdhsa_enable_private_segment 0
		.amdhsa_system_sgpr_workgroup_id_x 1
		.amdhsa_system_sgpr_workgroup_id_y 0
		.amdhsa_system_sgpr_workgroup_id_z 0
		.amdhsa_system_sgpr_workgroup_info 0
		.amdhsa_system_vgpr_workitem_id 0
		.amdhsa_next_free_vgpr 256
		.amdhsa_next_free_sgpr 102
		.amdhsa_accum_offset 256
		.amdhsa_reserve_vcc 1
		.amdhsa_float_round_mode_32 0
		.amdhsa_float_round_mode_16_64 0
		.amdhsa_float_denorm_mode_32 3
		.amdhsa_float_denorm_mode_16_64 3
		.amdhsa_dx10_clamp 1
		.amdhsa_ieee_mode 1
		.amdhsa_fp16_overflow 0
		.amdhsa_tg_split 0
		.amdhsa_exception_fp_ieee_invalid_op 0
		.amdhsa_exception_fp_denorm_src 0
		.amdhsa_exception_fp_ieee_div_zero 0
		.amdhsa_exception_fp_ieee_overflow 0
		.amdhsa_exception_fp_ieee_underflow 0
		.amdhsa_exception_fp_ieee_inexact 0
		.amdhsa_exception_int_div_zero 0
	.end_amdhsa_kernel

; #define LAS __attribute__((address_space(3)))
; __global__ void __launch_bounds__(NWAVES * 64, 2) mega_fwd(Args args) {
;     extern __shared__ __attribute__((aligned(16))) unsigned char lds[];
;     Frame F;
;     F.lds = (LAS unsigned char*)lds;
;     F.tid = threadIdx.x; F.lane = F.tid & 63; F.wave = __builtin_amdgcn_readfirstlane(F.tid >> 6);
;     F.G = gridDim.x; { const int bx = blockIdx.x; F.vcu = (F.G % 8 == 0) ? (bx % 8) * (F.G / 8) + bx / 8 : bx; }
;     unsigned char* ws = args.ws;
;     for (int u = F.tid; u < (LDS_BYTES - LDSCTL_OFF) / 4; u += NWAVES * 64) ((LAS unsigned*)(F.lds + LDSCTL_OFF))[u] = 0u;
;     __syncthreads();
amdhsa.kernels:
  - .agpr_count:     0
    .args:
      - .offset:         0
        .size:           136
        .value_kind:     by_value
      - .offset:         136
        .size:           4
        .value_kind:     hidden_block_count_x
      - .offset:         140
        .size:           4
        .value_kind:     hidden_block_count_y
      - .offset:         144
        .size:           4
        .value_kind:     hidden_block_count_z
      - .offset:         148
        .size:           2
        .value_kind:     hidden_group_size_x
      - .offset:         150
        .size:           2
        .value_kind:     hidden_group_size_y
      - .offset:         152
        .size:           2
        .value_kind:     hidden_group_size_z
      - .offset:         154
        .size:           2
        .value_kind:     hidden_remainder_x
      - .offset:         156
        .size:           2
        .value_kind:     hidden_remainder_y
      - .offset:         158
        .size:           2
        .value_kind:     hidden_remainder_z
      - .offset:         176
        .size:           8
        .value_kind:     hidden_global_offset_x
      - .offset:         184
        .size:           8
        .value_kind:     hidden_global_offset_y
      - .offset:         192
        .size:           8
        .value_kind:     hidden_global_offset_z
      - .offset:         200
        .size:           2
        .value_kind:     hidden_grid_dims
      - .offset:         256
        .size:           4
        .value_kind:     hidden_dynamic_lds_size
    .group_segment_fixed_size: 0
    .kernarg_segment_align: 8
    .kernarg_segment_size: 392
    .language:       OpenCL C
    .language_version:
      - 2
      - 0
    .max_flat_workgroup_size: 512
    .name:           _Z8mega_fwd4Args
    .private_segment_fixed_size: 0
    .sgpr_count:     108
    .sgpr_spill_count: 116
    .symbol:         _Z8mega_fwd4Args.kd
    .uniform_work_group_size: 1
    .uses_dynamic_stack: false
    .vgpr_count:     256
    .vgpr_spill_count: 0
    .wavefront_size: 64
